# PEER sub-key score MFMAs: key fragment reads run 3 MFMAs ahead through a 5-slot register ring instead of read-wait-MFMA on v[4:7]
# baseline (speedup 1.0000x reference)
.LBB0_1859:
	s_ashr_i32 s11, s10, 31
	s_lshl_b64 s[10:11], s[10:11], 18
	v_mov_b32_e32 v32, v206
	s_add_u32 s10, s14, s10
	s_addc_u32 s11, s15, s11
	v_ashrrev_i32_e32 v66, 3, v32
	s_ashr_i32 s9, s8, 31
	v_readlane_b32 s36, v248, 46
	v_ashrrev_i32_e32 v67, 31, v66
	s_lshl_b64 s[8:9], s[8:9], 18
	v_readlane_b32 s50, v248, 60
	v_lshlrev_b64 v[66:67], 11, v[66:67]
	v_lshlrev_b32_e32 v32, 4, v32
	v_readlane_b32 s51, v248, 61
	s_add_u32 s8, s50, s8
	v_lshl_add_u64 v[68:69], s[10:11], 0, v[66:67]
	v_and_b32_e32 v32, 0x70, v32
	s_addc_u32 s9, s51, s9
	v_lshl_add_u64 v[74:75], v[68:69], 0, v[32:33]
	v_lshl_add_u64 v[66:67], s[8:9], 0, v[66:67]
	s_mov_b32 s8, 0x10000
	v_add_co_u32_e32 v70, vcc, s8, v74
	s_mov_b32 s9, 0x20000
	s_nop 0
	v_addc_co_u32_e32 v71, vcc, 0, v75, vcc
	v_add_co_u32_e32 v76, vcc, s9, v74
	s_mov_b32 s10, 0x30000
	s_nop 0
	v_addc_co_u32_e32 v77, vcc, 0, v75, vcc
	v_lshl_add_u64 v[90:91], v[66:67], 0, v[32:33]
	global_load_dwordx4 v[66:69], v[74:75], off
	global_load_dwordx4 v[86:89], v[76:77], off
	v_cvt_pk_bf16_f32 v0, v0, v1
	global_load_dwordx4 v[70:73], v[70:71], off
	v_add_co_u32_e32 v74, vcc, s10, v74
	v_cvt_pk_bf16_f32 v1, v2, v3
	s_nop 0
	v_addc_co_u32_e32 v75, vcc, 0, v75, vcc
	global_load_dwordx4 v[94:97], v[74:75], off
	global_load_dwordx4 v[78:81], v[90:91], off
	v_add_co_u32_e32 v74, vcc, s8, v90
	s_movk_i32 s8, 0x108
	v_mul_lo_u32 v32, v187, s8
	v_lshl_add_u32 v32, v188, 1, v32
	ds_write2_b64 v32, v[126:127], v[128:129] offset1:1
	v_add_u32_e32 v126, 0x1080, v32
	ds_write2_b64 v126, v[102:103], v[104:105] offset1:1
	v_add_u32_e32 v102, 0x2100, v32
	v_addc_co_u32_e32 v75, vcc, 0, v91, vcc
	ds_write2_b64 v102, v[98:99], v[100:101] offset1:1
	v_add_u32_e32 v98, 0x3180, v32
	v_add_co_u32_e32 v82, vcc, s9, v90
	ds_write2_b64 v98, v[110:111], v[112:113] offset1:1
	v_add_u32_e32 v98, 0x4200, v32
	v_addc_co_u32_e32 v83, vcc, 0, v91, vcc
	ds_write2_b64 v98, v[106:107], v[108:109] offset1:1
	v_add_u32_e32 v98, 0x5280, v32
	v_cvt_pk_bf16_f32 v2, v4, v5
	v_and_b32_e32 v4, 31, v186
	s_waitcnt vmcnt(12)
	v_bfe_u32 v131, v186, 5, 1
	v_add_co_u32_e32 v90, vcc, s10, v90
	ds_write2_b64 v98, v[118:119], v[120:121] offset1:1
	v_add_u32_e32 v98, 0x6300, v32
	v_add_u32_e32 v32, 0x7380, v32
	v_mul_u32_u24_e32 v4, 0x108, v4
	v_addc_co_u32_e32 v91, vcc, 0, v91, vcc
	ds_write2_b64 v32, v[122:123], v[124:125] offset1:1
	v_cvt_pk_bf16_f32 v124, v12, v13
	v_lshl_add_u32 v12, v131, 3, v4
	global_load_dwordx4 v[74:77], v[74:75], off
	ds_write2_b64 v98, v[114:115], v[116:117] offset1:1
	global_load_dwordx4 v[82:85], v[82:83], off
	v_cvt_pk_bf16_f32 v3, v6, v7
	global_load_dwordx4 v[90:93], v[90:91], off
	v_cvt_pk_bf16_f32 v122, v8, v9
	v_cvt_pk_bf16_f32 v123, v10, v11
	s_waitcnt lgkmcnt(0)
	s_barrier
	v_add_u32_e32 v244, 0x2000, v12
	v_add_u32_e32 v245, 0x4000, v12
	v_add_u32_e32 v246, 0x6000, v12
	ds_read2_b64 v[224:227], v12 offset1:2
	ds_read2_b64 v[228:231], v12 offset0:4 offset1:6
	ds_read2_b64 v[232:235], v12 offset0:8 offset1:10
	s_nop 0
	s_nop 0
	v_cvt_pk_bf16_f32 v102, v50, v51
	v_cvt_pk_bf16_f32 v103, v52, v53
	v_cvt_pk_bf16_f32 v104, v54, v55
	v_cvt_pk_bf16_f32 v105, v56, v57
	v_cvt_pk_bf16_f32 v98, v58, v59
	v_cvt_pk_bf16_f32 v99, v60, v61
	v_cvt_pk_bf16_f32 v100, v62, v63
	v_cvt_pk_bf16_f32 v101, v64, v65
	ds_read2_b64 v[236:239], v12 offset0:12 offset1:14
	s_waitcnt lgkmcnt(3)
	v_mfma_f32_32x32x16_bf16 v[50:65], v[224:227], v[0:3], 0
	v_cvt_pk_bf16_f32 v125, v14, v15
	s_nop 0
	v_cvt_pk_bf16_f32 v118, v16, v17
	v_cvt_pk_bf16_f32 v119, v18, v19
	v_cvt_pk_bf16_f32 v120, v20, v21
	v_cvt_pk_bf16_f32 v121, v22, v23
	v_cvt_pk_bf16_f32 v114, v24, v25
	ds_read2_b64 v[240:243], v12 offset0:16 offset1:18
	s_waitcnt lgkmcnt(3)
	v_mfma_f32_32x32x16_bf16 v[50:65], v[228:231], v[122:125], v[50:65]
	v_cvt_pk_bf16_f32 v115, v26, v27
	v_cvt_pk_bf16_f32 v116, v28, v29
	v_cvt_pk_bf16_f32 v117, v30, v31
	v_cvt_pk_bf16_f32 v110, v34, v35
	v_cvt_pk_bf16_f32 v111, v36, v37
	v_cvt_pk_bf16_f32 v112, v38, v39
	v_cvt_pk_bf16_f32 v113, v40, v41
	ds_read2_b64 v[224:227], v12 offset0:20 offset1:22
	s_waitcnt lgkmcnt(3)
	v_mfma_f32_32x32x16_bf16 v[50:65], v[232:235], v[118:121], v[50:65]
	s_nop 0
	v_cvt_pk_bf16_f32 v106, v42, v43
	v_cvt_pk_bf16_f32 v107, v44, v45
	v_cvt_pk_bf16_f32 v108, v46, v47
	v_cvt_pk_bf16_f32 v109, v48, v49
	v_add_u32_e32 v8, 0x2000, v12
	v_add_u32_e32 v32, 0x6000, v12
	ds_read2_b64 v[228:231], v12 offset0:24 offset1:26
	s_waitcnt lgkmcnt(3)
	v_mfma_f32_32x32x16_bf16 v[50:65], v[236:239], v[114:117], v[50:65]
	s_nop 0
	s_nop 0
	s_movk_i32 s8, 0x7f
	v_and_b32_e32 v130, 63, v186
	v_readlane_b32 s37, v248, 47
	v_readlane_b32 s38, v248, 48
	v_readlane_b32 s39, v248, 49
	ds_read2_b64 v[232:235], v12 offset0:28 offset1:30
	s_waitcnt lgkmcnt(3)
	v_mfma_f32_32x32x16_bf16 v[50:65], v[240:243], v[110:113], v[50:65]
	s_nop 0
	v_readlane_b32 s40, v248, 50
	v_readlane_b32 s41, v248, 51
	v_readlane_b32 s42, v248, 52
	v_readlane_b32 s43, v248, 53
	v_readlane_b32 s44, v248, 54
	v_readlane_b32 s45, v248, 55
	ds_read2_b64 v[236:239], v244 offset0:32 offset1:34
	s_waitcnt lgkmcnt(3)
	v_mfma_f32_32x32x16_bf16 v[50:65], v[224:227], v[106:109], v[50:65]
	s_nop 0
	v_readlane_b32 s46, v248, 56
	v_readlane_b32 s47, v248, 57
	v_readlane_b32 s48, v248, 58
	v_readlane_b32 s49, v248, 59
	ds_read2_b64 v[240:243], v244 offset0:36 offset1:38
	s_waitcnt lgkmcnt(3)
	v_mfma_f32_32x32x16_bf16 v[50:65], v[228:231], v[102:105], v[50:65]
	s_nop 0
	ds_read2_b64 v[224:227], v244 offset0:40 offset1:42
	s_waitcnt lgkmcnt(3)
	v_mfma_f32_32x32x16_bf16 v[50:65], v[232:235], v[98:101], v[50:65]
	s_nop 0
	ds_read2_b64 v[228:231], v244 offset0:44 offset1:46
	s_waitcnt lgkmcnt(3)
	v_mfma_f32_32x32x16_bf16 v[34:49], v[236:239], v[0:3], 0
	s_nop 0
	s_nop 7
	v_and_b32_e32 v50, 0xffffff80, v50
	v_and_b32_e32 v51, 0xffffff80, v51
	ds_read2_b64 v[232:235], v244 offset0:48 offset1:50
	s_waitcnt lgkmcnt(3)
	v_mfma_f32_32x32x16_bf16 v[34:49], v[240:243], v[122:125], v[34:49]
	s_nop 0
	ds_read2_b64 v[236:239], v244 offset0:52 offset1:54
	s_waitcnt lgkmcnt(3)
	v_mfma_f32_32x32x16_bf16 v[34:49], v[224:227], v[118:121], v[34:49]
	s_nop 0
	ds_read2_b64 v[240:243], v244 offset0:56 offset1:58
	s_waitcnt lgkmcnt(3)
	v_mfma_f32_32x32x16_bf16 v[34:49], v[228:231], v[114:117], v[34:49]
	s_nop 0
	ds_read2_b64 v[224:227], v244 offset0:60 offset1:62
	s_waitcnt lgkmcnt(3)
	v_mfma_f32_32x32x16_bf16 v[34:49], v[232:235], v[110:113], v[34:49]
	s_nop 0
	ds_read2_b64 v[228:231], v245 offset0:64 offset1:66
	s_waitcnt lgkmcnt(3)
	v_mfma_f32_32x32x16_bf16 v[34:49], v[236:239], v[106:109], v[34:49]
	s_nop 0
	ds_read2_b64 v[232:235], v245 offset0:68 offset1:70
	s_waitcnt lgkmcnt(3)
	v_mfma_f32_32x32x16_bf16 v[34:49], v[240:243], v[102:105], v[34:49]
	s_nop 0
	v_add_u32_e32 v8, 0x4000, v12
	ds_read2_b64 v[236:239], v245 offset0:72 offset1:74
	s_waitcnt lgkmcnt(3)
	v_mfma_f32_32x32x16_bf16 v[34:49], v[224:227], v[98:101], v[34:49]
	s_nop 0
	ds_read2_b64 v[240:243], v245 offset0:76 offset1:78
	s_waitcnt lgkmcnt(3)
	v_mfma_f32_32x32x16_bf16 v[16:31], v[228:231], v[0:3], 0
	s_nop 0
	s_nop 7
	v_and_b32_e32 v34, 0xffffff80, v34
	v_and_b32_e32 v35, 0xffffff80, v35
	ds_read2_b64 v[224:227], v245 offset0:80 offset1:82
	s_waitcnt lgkmcnt(3)
	v_mfma_f32_32x32x16_bf16 v[16:31], v[232:235], v[122:125], v[16:31]
	s_nop 0
	ds_read2_b64 v[228:231], v245 offset0:84 offset1:86
	s_waitcnt lgkmcnt(3)
	v_mfma_f32_32x32x16_bf16 v[16:31], v[236:239], v[118:121], v[16:31]
	s_nop 0
	ds_read2_b64 v[232:235], v245 offset0:88 offset1:90
	s_waitcnt lgkmcnt(3)
	v_mfma_f32_32x32x16_bf16 v[16:31], v[240:243], v[114:117], v[16:31]
	s_nop 0
	ds_read2_b64 v[236:239], v245 offset0:92 offset1:94
	s_waitcnt lgkmcnt(3)
	v_mfma_f32_32x32x16_bf16 v[16:31], v[224:227], v[110:113], v[16:31]
	s_nop 0
	ds_read2_b64 v[240:243], v246 offset0:96 offset1:98
	s_waitcnt lgkmcnt(3)
	v_mfma_f32_32x32x16_bf16 v[16:31], v[228:231], v[106:109], v[16:31]
	s_nop 0
	ds_read2_b64 v[224:227], v246 offset0:100 offset1:102
	s_waitcnt lgkmcnt(3)
	v_mfma_f32_32x32x16_bf16 v[16:31], v[232:235], v[102:105], v[16:31]
	s_nop 0
	ds_read2_b64 v[228:231], v246 offset0:104 offset1:106
	s_waitcnt lgkmcnt(3)
	v_mfma_f32_32x32x16_bf16 v[16:31], v[236:239], v[98:101], v[16:31]
	s_nop 0
	ds_read2_b64 v[232:235], v246 offset0:108 offset1:110
	s_waitcnt lgkmcnt(3)
	v_mfma_f32_32x32x16_bf16 v[0:15], v[240:243], v[0:3], 0
	s_nop 8
	v_and_b32_e32 v16, 0xffffff80, v16
	v_and_b32_e32 v17, 0xffffff80, v17
	ds_read2_b64 v[236:239], v246 offset0:112 offset1:114
	s_waitcnt lgkmcnt(3)
	v_mfma_f32_32x32x16_bf16 v[0:15], v[224:227], v[122:125], v[0:15]
	s_nop 0
	ds_read2_b64 v[240:243], v246 offset0:116 offset1:118
	s_waitcnt lgkmcnt(3)
	v_mfma_f32_32x32x16_bf16 v[0:15], v[228:231], v[118:121], v[0:15]
	s_nop 0
	ds_read2_b64 v[224:227], v246 offset0:120 offset1:122
	s_waitcnt lgkmcnt(3)
	v_mfma_f32_32x32x16_bf16 v[0:15], v[232:235], v[114:117], v[0:15]
	s_nop 0
	ds_read2_b64 v[228:231], v246 offset0:124 offset1:126
	s_waitcnt lgkmcnt(3)
	v_mfma_f32_32x32x16_bf16 v[0:15], v[236:239], v[110:113], v[0:15]
	s_nop 0
	s_waitcnt lgkmcnt(2)
	v_mfma_f32_32x32x16_bf16 v[0:15], v[240:243], v[106:109], v[0:15]
	s_nop 0
	s_waitcnt lgkmcnt(1)
	v_mfma_f32_32x32x16_bf16 v[0:15], v[224:227], v[102:105], v[0:15]
	s_nop 0
	v_lshlrev_b32_e32 v32, 2, v131
	v_bitop3_b32 v50, v50, s8, v32 bitop3:0x36
	s_mov_b32 s8, 0xff61b1e6
	v_sub_u32_e32 v51, v51, v32
	v_add_u32_e32 v51, 0x7e, v51
	v_sub_u32_e32 v34, v34, v32
	s_waitcnt lgkmcnt(0)
	v_mfma_f32_32x32x16_bf16 v[0:15], v[228:231], v[98:101], v[0:15]
	v_med3_f32 v98, v50, s8, s8
	v_max_f32_e32 v50, v50, v50
	v_max_f32_e32 v50, 0xff61b1e6, v50
	v_med3_f32 v99, v98, v98, v51
	v_med3_f32 v98, v50, v98, v51
	v_max_f32_e32 v51, v51, v51
	v_max_f32_e32 v50, v50, v51
	v_and_b32_e32 v51, 0xffffff80, v52
	v_sub_u32_e32 v51, v51, v32
	v_add_u32_e32 v51, 0x7d, v51
	v_med3_f32 v52, v99, v99, v51
	v_med3_f32 v99, v98, v99, v51
	v_med3_f32 v98, v50, v98, v51
	v_max_f32_e32 v51, v51, v51
	v_max_f32_e32 v50, v50, v51
	v_and_b32_e32 v51, 0xffffff80, v53
	v_sub_u32_e32 v51, v51, v32
	v_add_u32_e32 v51, 0x7c, v51
	v_med3_f32 v53, v52, v52, v51
	v_med3_f32 v52, v99, v52, v51
	v_med3_f32 v99, v98, v99, v51
	v_med3_f32 v98, v50, v98, v51
	v_max_f32_e32 v51, v51, v51
	v_max_f32_e32 v50, v50, v51
	v_and_b32_e32 v51, 0xffffff80, v54
	v_sub_u32_e32 v51, v51, v32
	v_add_u32_e32 v51, 0x77, v51
	v_med3_f32 v54, v53, v53, v51
	v_med3_f32 v53, v52, v53, v51
	v_med3_f32 v52, v99, v52, v51
	v_med3_f32 v99, v98, v99, v51
	v_med3_f32 v98, v50, v98, v51
	v_max_f32_e32 v51, v51, v51
	v_max_f32_e32 v50, v50, v51
	v_and_b32_e32 v51, 0xffffff80, v55
	v_sub_u32_e32 v51, v51, v32
	v_add_u32_e32 v51, 0x76, v51
	v_med3_f32 v55, v54, v54, v51
	v_med3_f32 v54, v53, v54, v51
	v_med3_f32 v53, v52, v53, v51
	v_med3_f32 v52, v99, v52, v51
	v_med3_f32 v99, v98, v99, v51
	v_med3_f32 v98, v50, v98, v51
	v_max_f32_e32 v51, v51, v51
	v_max_f32_e32 v50, v50, v51
	v_and_b32_e32 v51, 0xffffff80, v56
	v_sub_u32_e32 v51, v51, v32
	v_add_u32_e32 v51, 0x75, v51
	v_med3_f32 v56, v55, v55, v51
	v_med3_f32 v55, v54, v55, v51
	v_med3_f32 v54, v53, v54, v51
	v_med3_f32 v53, v52, v53, v51
	v_med3_f32 v52, v99, v52, v51
	v_med3_f32 v99, v98, v99, v51
	v_med3_f32 v98, v50, v98, v51
	v_max_f32_e32 v51, v51, v51
	v_max_f32_e32 v50, v50, v51
	v_and_b32_e32 v51, 0xffffff80, v57
	v_sub_u32_e32 v51, v51, v32
	v_add_u32_e32 v51, 0x74, v51
	v_med3_f32 v57, v56, v56, v51
	v_med3_f32 v56, v55, v56, v51
	v_med3_f32 v55, v54, v55, v51
	v_med3_f32 v54, v53, v54, v51
	v_med3_f32 v53, v52, v53, v51
	v_med3_f32 v52, v99, v52, v51
	v_med3_f32 v99, v98, v99, v51
	v_med3_f32 v98, v50, v98, v51
	v_max_f32_e32 v51, v51, v51
	v_max_f32_e32 v50, v50, v51
	v_and_b32_e32 v51, 0xffffff80, v58
	v_sub_u32_e32 v51, v51, v32
	v_add_u32_e32 v51, 0x6f, v51
	v_med3_f32 v58, v57, v57, v51
	v_med3_f32 v57, v56, v57, v51
	v_med3_f32 v56, v55, v56, v51
	v_med3_f32 v55, v54, v55, v51
	v_med3_f32 v54, v53, v54, v51
	v_med3_f32 v53, v52, v53, v51
	v_med3_f32 v52, v99, v52, v51
	v_med3_f32 v99, v98, v99, v51
	v_med3_f32 v98, v50, v98, v51
	v_max_f32_e32 v51, v51, v51
	v_max_f32_e32 v50, v50, v51
	v_and_b32_e32 v51, 0xffffff80, v59
	v_sub_u32_e32 v51, v51, v32
	v_add_u32_e32 v51, 0x6e, v51
	v_med3_f32 v59, v58, v58, v51
	v_med3_f32 v58, v57, v58, v51
	v_med3_f32 v57, v56, v57, v51
	v_med3_f32 v56, v55, v56, v51
	v_med3_f32 v55, v54, v55, v51
	v_med3_f32 v54, v53, v54, v51
	v_med3_f32 v53, v52, v53, v51
	v_med3_f32 v52, v99, v52, v51
	v_med3_f32 v99, v98, v99, v51
	v_med3_f32 v98, v50, v98, v51
	v_max_f32_e32 v51, v51, v51
	v_max_f32_e32 v50, v50, v51
	v_and_b32_e32 v51, 0xffffff80, v60
	v_sub_u32_e32 v51, v51, v32
	v_add_u32_e32 v51, 0x6d, v51
	v_med3_f32 v60, v59, v59, v51
	v_med3_f32 v59, v58, v59, v51
	v_med3_f32 v58, v57, v58, v51
	v_med3_f32 v57, v56, v57, v51
	v_med3_f32 v56, v55, v56, v51
	v_med3_f32 v55, v54, v55, v51
	v_med3_f32 v54, v53, v54, v51
	v_med3_f32 v53, v52, v53, v51
	v_med3_f32 v52, v99, v52, v51
	v_med3_f32 v99, v98, v99, v51
	v_med3_f32 v98, v50, v98, v51
	v_max_f32_e32 v51, v51, v51
	v_max_f32_e32 v50, v50, v51
	v_and_b32_e32 v51, 0xffffff80, v61
	v_sub_u32_e32 v51, v51, v32
	v_add_u32_e32 v51, 0x6c, v51
	v_med3_f32 v61, v60, v60, v51
	v_med3_f32 v60, v59, v60, v51
	v_med3_f32 v59, v58, v59, v51
	v_med3_f32 v58, v57, v58, v51
	v_med3_f32 v57, v56, v57, v51
	v_med3_f32 v56, v55, v56, v51
	v_med3_f32 v55, v54, v55, v51
	v_med3_f32 v54, v53, v54, v51
	v_med3_f32 v53, v52, v53, v51
	v_med3_f32 v52, v99, v52, v51
	v_med3_f32 v99, v98, v99, v51
	v_med3_f32 v98, v50, v98, v51
	v_max_f32_e32 v51, v51, v51
	v_max_f32_e32 v50, v50, v51
	v_and_b32_e32 v51, 0xffffff80, v62
	v_sub_u32_e32 v51, v51, v32
	v_add_u32_e32 v51, 0x67, v51
	v_med3_f32 v62, v61, v61, v51
	v_med3_f32 v61, v60, v61, v51
	v_med3_f32 v60, v59, v60, v51
	v_med3_f32 v59, v58, v59, v51
	v_med3_f32 v58, v57, v58, v51
	v_med3_f32 v57, v56, v57, v51
	v_med3_f32 v56, v55, v56, v51
	v_med3_f32 v55, v54, v55, v51
	v_med3_f32 v54, v53, v54, v51
	v_med3_f32 v53, v52, v53, v51
	v_med3_f32 v52, v99, v52, v51
	v_med3_f32 v99, v98, v99, v51
	v_med3_f32 v98, v50, v98, v51
	v_max_f32_e32 v51, v51, v51
	v_max_f32_e32 v50, v50, v51
	v_and_b32_e32 v51, 0xffffff80, v63
	v_sub_u32_e32 v51, v51, v32
	v_add_u32_e32 v51, 0x66, v51
	v_med3_f32 v63, v62, v62, v51
	v_med3_f32 v62, v61, v62, v51
	v_med3_f32 v61, v60, v61, v51
	v_med3_f32 v60, v59, v60, v51
	v_med3_f32 v59, v58, v59, v51
	v_med3_f32 v58, v57, v58, v51
	v_med3_f32 v57, v56, v57, v51
	v_med3_f32 v56, v55, v56, v51
	v_med3_f32 v55, v54, v55, v51
	v_med3_f32 v54, v53, v54, v51
	v_med3_f32 v53, v52, v53, v51
	v_med3_f32 v52, v99, v52, v51
	v_med3_f32 v99, v98, v99, v51
	v_med3_f32 v98, v50, v98, v51
	v_max_f32_e32 v51, v51, v51
	v_max_f32_e32 v50, v50, v51
	v_and_b32_e32 v51, 0xffffff80, v64
	v_sub_u32_e32 v51, v51, v32
	v_add_u32_e32 v51, 0x65, v51
	v_med3_f32 v64, v63, v63, v51
	v_med3_f32 v63, v62, v63, v51
	v_med3_f32 v62, v61, v62, v51
	v_med3_f32 v61, v60, v61, v51
	v_med3_f32 v60, v59, v60, v51
	v_med3_f32 v59, v58, v59, v51
	v_med3_f32 v58, v57, v58, v51
	v_med3_f32 v57, v56, v57, v51
	v_med3_f32 v56, v55, v56, v51
	v_med3_f32 v55, v54, v55, v51
	v_med3_f32 v54, v53, v54, v51
	v_med3_f32 v53, v52, v53, v51
	v_med3_f32 v52, v99, v52, v51
	v_med3_f32 v99, v98, v99, v51
	v_med3_f32 v98, v50, v98, v51
	v_max_f32_e32 v51, v51, v51
	v_max_f32_e32 v50, v50, v51
	v_and_b32_e32 v51, 0xffffff80, v65
	v_sub_u32_e32 v51, v51, v32
	v_add_u32_e32 v51, 0x64, v51
	v_med3_f32 v64, v63, v64, v51
	v_med3_f32 v63, v62, v63, v51
	v_med3_f32 v62, v61, v62, v51
	v_med3_f32 v61, v60, v61, v51
	v_med3_f32 v60, v59, v60, v51
	v_med3_f32 v59, v58, v59, v51
	v_med3_f32 v58, v57, v58, v51
	v_med3_f32 v57, v56, v57, v51
	v_med3_f32 v56, v55, v56, v51
	v_med3_f32 v55, v54, v55, v51
	v_med3_f32 v54, v53, v54, v51
	v_med3_f32 v53, v52, v53, v51
	v_med3_f32 v52, v99, v52, v51
	v_med3_f32 v65, v98, v99, v51
	v_med3_f32 v98, v50, v98, v51
	v_max_f32_e32 v51, v51, v51
	v_max_f32_e32 v50, v50, v51
	v_add_u32_e32 v34, 0x5f, v34
	v_med3_f32 v51, v63, v64, v34
	v_med3_f32 v63, v62, v63, v34
	v_med3_f32 v62, v61, v62, v34
	v_med3_f32 v61, v60, v61, v34
	v_med3_f32 v60, v59, v60, v34
	v_med3_f32 v59, v58, v59, v34
	v_med3_f32 v58, v57, v58, v34
	v_med3_f32 v57, v56, v57, v34
	v_med3_f32 v56, v55, v56, v34
	v_med3_f32 v55, v54, v55, v34
	v_med3_f32 v54, v53, v54, v34
	v_med3_f32 v53, v52, v53, v34
	v_med3_f32 v52, v65, v52, v34
	v_med3_f32 v64, v98, v65, v34
	v_med3_f32 v65, v50, v98, v34
	v_max_f32_e32 v34, v34, v34
	v_sub_u32_e32 v35, v35, v32
	v_max_f32_e32 v34, v50, v34
	v_add_u32_e32 v35, 0x5e, v35
	v_med3_f32 v50, v63, v51, v35
	v_med3_f32 v51, v62, v63, v35
	v_med3_f32 v62, v61, v62, v35
	v_med3_f32 v61, v60, v61, v35
	v_med3_f32 v60, v59, v60, v35
	v_med3_f32 v59, v58, v59, v35
	v_med3_f32 v58, v57, v58, v35
	v_med3_f32 v57, v56, v57, v35
	v_med3_f32 v56, v55, v56, v35
	v_med3_f32 v55, v54, v55, v35
	v_med3_f32 v54, v53, v54, v35
	v_med3_f32 v53, v52, v53, v35
	v_med3_f32 v52, v64, v52, v35
	v_med3_f32 v63, v65, v64, v35
	v_med3_f32 v64, v34, v65, v35
	v_max_f32_e32 v35, v35, v35
	v_max_f32_e32 v34, v34, v35
	v_and_b32_e32 v35, 0xffffff80, v36
	v_sub_u32_e32 v35, v35, v32
	v_add_u32_e32 v35, 0x5d, v35
	v_med3_f32 v36, v51, v50, v35
	v_med3_f32 v50, v62, v51, v35
	v_med3_f32 v51, v61, v62, v35
	v_med3_f32 v61, v60, v61, v35
	v_med3_f32 v60, v59, v60, v35
	v_med3_f32 v59, v58, v59, v35
	v_med3_f32 v58, v57, v58, v35
	v_med3_f32 v57, v56, v57, v35
	v_med3_f32 v56, v55, v56, v35
	v_med3_f32 v55, v54, v55, v35
	v_med3_f32 v54, v53, v54, v35
	v_med3_f32 v53, v52, v53, v35
	v_med3_f32 v52, v63, v52, v35
	v_med3_f32 v62, v64, v63, v35
	v_med3_f32 v63, v34, v64, v35
	v_max_f32_e32 v35, v35, v35
	v_max_f32_e32 v34, v34, v35
	v_and_b32_e32 v35, 0xffffff80, v37
	v_sub_u32_e32 v35, v35, v32
	v_add_u32_e32 v35, 0x5c, v35
	v_med3_f32 v36, v50, v36, v35
	v_med3_f32 v37, v51, v50, v35
	v_med3_f32 v50, v61, v51, v35
	v_med3_f32 v51, v60, v61, v35
	v_med3_f32 v60, v59, v60, v35
	v_med3_f32 v59, v58, v59, v35
	v_med3_f32 v58, v57, v58, v35
	v_med3_f32 v57, v56, v57, v35
	v_med3_f32 v56, v55, v56, v35
	v_med3_f32 v55, v54, v55, v35
	v_med3_f32 v54, v53, v54, v35
	v_med3_f32 v53, v52, v53, v35
	v_med3_f32 v52, v62, v52, v35
	v_med3_f32 v61, v63, v62, v35
	v_med3_f32 v62, v34, v63, v35
	v_max_f32_e32 v35, v35, v35
	v_max_f32_e32 v34, v34, v35
	v_and_b32_e32 v35, 0xffffff80, v38
	v_sub_u32_e32 v35, v35, v32
	v_add_u32_e32 v35, 0x57, v35
	v_med3_f32 v36, v37, v36, v35
	v_med3_f32 v37, v50, v37, v35
	v_med3_f32 v38, v51, v50, v35
	v_med3_f32 v50, v60, v51, v35
	v_med3_f32 v51, v59, v60, v35
	v_med3_f32 v59, v58, v59, v35
	v_med3_f32 v58, v57, v58, v35
	v_med3_f32 v57, v56, v57, v35
	v_med3_f32 v56, v55, v56, v35
	v_med3_f32 v55, v54, v55, v35
	v_med3_f32 v54, v53, v54, v35
	v_med3_f32 v53, v52, v53, v35
	v_med3_f32 v52, v61, v52, v35
	v_med3_f32 v60, v62, v61, v35
	v_med3_f32 v61, v34, v62, v35
	v_max_f32_e32 v35, v35, v35
	v_max_f32_e32 v34, v34, v35
	v_and_b32_e32 v35, 0xffffff80, v39
	v_sub_u32_e32 v35, v35, v32
	v_add_u32_e32 v35, 0x56, v35
	v_med3_f32 v36, v37, v36, v35
	v_med3_f32 v37, v38, v37, v35
	v_med3_f32 v38, v50, v38, v35
	v_med3_f32 v39, v51, v50, v35
	v_med3_f32 v50, v59, v51, v35
	v_med3_f32 v51, v58, v59, v35
	v_med3_f32 v58, v57, v58, v35
	v_med3_f32 v57, v56, v57, v35
	v_med3_f32 v56, v55, v56, v35
	v_med3_f32 v55, v54, v55, v35
	v_med3_f32 v54, v53, v54, v35
	v_med3_f32 v53, v52, v53, v35
	v_med3_f32 v52, v60, v52, v35
	v_med3_f32 v59, v61, v60, v35
	v_med3_f32 v60, v34, v61, v35
	v_max_f32_e32 v35, v35, v35
	v_max_f32_e32 v34, v34, v35
	v_and_b32_e32 v35, 0xffffff80, v40
	v_sub_u32_e32 v35, v35, v32
	v_add_u32_e32 v35, 0x55, v35
	v_med3_f32 v36, v37, v36, v35
	v_med3_f32 v37, v38, v37, v35
	v_med3_f32 v38, v39, v38, v35
	v_med3_f32 v39, v50, v39, v35
	v_med3_f32 v40, v51, v50, v35
	v_med3_f32 v50, v58, v51, v35
	v_med3_f32 v51, v57, v58, v35
	v_med3_f32 v57, v56, v57, v35
	v_med3_f32 v56, v55, v56, v35
	v_med3_f32 v55, v54, v55, v35
	v_med3_f32 v54, v53, v54, v35
	v_med3_f32 v53, v52, v53, v35
	v_med3_f32 v52, v59, v52, v35
	v_med3_f32 v58, v60, v59, v35
	v_med3_f32 v59, v34, v60, v35
	v_max_f32_e32 v35, v35, v35
	v_max_f32_e32 v34, v34, v35
	v_and_b32_e32 v35, 0xffffff80, v41
	v_sub_u32_e32 v35, v35, v32
	v_add_u32_e32 v35, 0x54, v35
	v_med3_f32 v36, v37, v36, v35
	v_med3_f32 v37, v38, v37, v35
	v_med3_f32 v38, v39, v38, v35
	v_med3_f32 v39, v40, v39, v35
	v_med3_f32 v40, v50, v40, v35
	v_med3_f32 v41, v51, v50, v35
	v_med3_f32 v50, v57, v51, v35
	v_med3_f32 v51, v56, v57, v35
	v_med3_f32 v56, v55, v56, v35
	v_med3_f32 v55, v54, v55, v35
	v_med3_f32 v54, v53, v54, v35
	v_med3_f32 v53, v52, v53, v35
	v_med3_f32 v52, v58, v52, v35
	v_med3_f32 v57, v59, v58, v35
	v_med3_f32 v58, v34, v59, v35
	v_max_f32_e32 v35, v35, v35
	v_max_f32_e32 v34, v34, v35
	v_and_b32_e32 v35, 0xffffff80, v42
	v_sub_u32_e32 v35, v35, v32
	v_add_u32_e32 v35, 0x4f, v35
	v_med3_f32 v36, v37, v36, v35
	v_med3_f32 v37, v38, v37, v35
	v_med3_f32 v38, v39, v38, v35
	v_med3_f32 v39, v40, v39, v35
	v_med3_f32 v40, v41, v40, v35
	v_med3_f32 v41, v50, v41, v35
	v_med3_f32 v42, v51, v50, v35
	v_med3_f32 v50, v56, v51, v35
	v_med3_f32 v51, v55, v56, v35
	v_med3_f32 v55, v54, v55, v35
	v_med3_f32 v54, v53, v54, v35
	v_med3_f32 v53, v52, v53, v35
	v_med3_f32 v52, v57, v52, v35
	v_med3_f32 v56, v58, v57, v35
	v_med3_f32 v57, v34, v58, v35
	v_max_f32_e32 v35, v35, v35
	v_max_f32_e32 v34, v34, v35
	v_and_b32_e32 v35, 0xffffff80, v43
	v_sub_u32_e32 v35, v35, v32
	v_add_u32_e32 v35, 0x4e, v35
	v_med3_f32 v36, v37, v36, v35
	v_med3_f32 v37, v38, v37, v35
	v_med3_f32 v38, v39, v38, v35
	v_med3_f32 v39, v40, v39, v35
	v_med3_f32 v40, v41, v40, v35
	v_med3_f32 v41, v42, v41, v35
	v_med3_f32 v42, v50, v42, v35
	v_med3_f32 v43, v51, v50, v35
	v_med3_f32 v50, v55, v51, v35
	v_med3_f32 v51, v54, v55, v35
	v_med3_f32 v54, v53, v54, v35
	v_med3_f32 v53, v52, v53, v35
	v_med3_f32 v52, v56, v52, v35
	v_med3_f32 v55, v57, v56, v35
	v_med3_f32 v56, v34, v57, v35
	v_max_f32_e32 v35, v35, v35
	v_max_f32_e32 v34, v34, v35
	v_and_b32_e32 v35, 0xffffff80, v44
	v_sub_u32_e32 v35, v35, v32
	v_add_u32_e32 v35, 0x4d, v35
	v_med3_f32 v36, v37, v36, v35
	v_med3_f32 v37, v38, v37, v35
	v_med3_f32 v38, v39, v38, v35
	v_med3_f32 v39, v40, v39, v35
	v_med3_f32 v40, v41, v40, v35
	v_med3_f32 v41, v42, v41, v35
	v_med3_f32 v42, v43, v42, v35
	v_med3_f32 v43, v50, v43, v35
	v_med3_f32 v44, v51, v50, v35
	v_med3_f32 v50, v54, v51, v35
	v_med3_f32 v51, v53, v54, v35
	v_med3_f32 v53, v52, v53, v35
	v_med3_f32 v52, v55, v52, v35
	v_med3_f32 v54, v56, v55, v35
	v_med3_f32 v55, v34, v56, v35
	v_max_f32_e32 v35, v35, v35
	v_max_f32_e32 v34, v34, v35
	v_and_b32_e32 v35, 0xffffff80, v45
	v_sub_u32_e32 v35, v35, v32
	v_add_u32_e32 v35, 0x4c, v35
	v_med3_f32 v36, v37, v36, v35
	v_med3_f32 v37, v38, v37, v35
	v_med3_f32 v38, v39, v38, v35
	v_med3_f32 v39, v40, v39, v35
	v_med3_f32 v40, v41, v40, v35
	v_med3_f32 v41, v42, v41, v35
	v_med3_f32 v42, v43, v42, v35
	v_med3_f32 v43, v44, v43, v35
	v_med3_f32 v44, v50, v44, v35
	v_med3_f32 v45, v51, v50, v35
	v_med3_f32 v50, v53, v51, v35
	v_med3_f32 v51, v52, v53, v35
	v_med3_f32 v52, v54, v52, v35
	v_med3_f32 v53, v55, v54, v35
	v_med3_f32 v54, v34, v55, v35
	v_max_f32_e32 v35, v35, v35
	v_max_f32_e32 v34, v34, v35
	v_and_b32_e32 v35, 0xffffff80, v46
	v_sub_u32_e32 v35, v35, v32
	v_add_u32_e32 v35, 0x47, v35
	v_med3_f32 v36, v37, v36, v35
	v_med3_f32 v37, v38, v37, v35
	v_med3_f32 v38, v39, v38, v35
	v_med3_f32 v39, v40, v39, v35
	v_med3_f32 v40, v41, v40, v35
	v_med3_f32 v41, v42, v41, v35
	v_med3_f32 v42, v43, v42, v35
	v_med3_f32 v43, v44, v43, v35
	v_med3_f32 v44, v45, v44, v35
	v_med3_f32 v45, v50, v45, v35
	v_med3_f32 v46, v51, v50, v35
	v_med3_f32 v50, v52, v51, v35
	v_med3_f32 v51, v53, v52, v35
	v_med3_f32 v52, v54, v53, v35
	v_med3_f32 v53, v34, v54, v35
	v_max_f32_e32 v35, v35, v35
	v_max_f32_e32 v34, v34, v35
	v_and_b32_e32 v35, 0xffffff80, v47
	v_sub_u32_e32 v35, v35, v32
	v_add_u32_e32 v35, 0x46, v35
	v_med3_f32 v36, v37, v36, v35
	v_med3_f32 v37, v38, v37, v35
	v_med3_f32 v38, v39, v38, v35
	v_med3_f32 v39, v40, v39, v35
	v_med3_f32 v40, v41, v40, v35
	v_med3_f32 v41, v42, v41, v35
	v_med3_f32 v42, v43, v42, v35
	v_med3_f32 v43, v44, v43, v35
	v_med3_f32 v44, v45, v44, v35
	v_med3_f32 v45, v46, v45, v35
	v_med3_f32 v46, v50, v46, v35
	v_med3_f32 v47, v51, v50, v35
	v_med3_f32 v50, v52, v51, v35
	v_med3_f32 v51, v53, v52, v35
	v_med3_f32 v52, v34, v53, v35
	v_max_f32_e32 v35, v35, v35
	v_max_f32_e32 v34, v34, v35
	v_and_b32_e32 v35, 0xffffff80, v48
	v_sub_u32_e32 v35, v35, v32
	v_add_u32_e32 v35, 0x45, v35
	v_med3_f32 v36, v37, v36, v35
	v_med3_f32 v37, v38, v37, v35
	v_med3_f32 v38, v39, v38, v35
	v_med3_f32 v39, v40, v39, v35
	v_med3_f32 v40, v41, v40, v35
	v_med3_f32 v41, v42, v41, v35
	v_med3_f32 v42, v43, v42, v35
	v_med3_f32 v43, v44, v43, v35
	v_med3_f32 v44, v45, v44, v35
	v_med3_f32 v45, v46, v45, v35
	v_med3_f32 v46, v47, v46, v35
	v_med3_f32 v47, v50, v47, v35
	v_med3_f32 v48, v51, v50, v35
	v_med3_f32 v50, v52, v51, v35
	v_med3_f32 v51, v34, v52, v35
	v_max_f32_e32 v35, v35, v35
	v_max_f32_e32 v34, v34, v35
	v_and_b32_e32 v35, 0xffffff80, v49
	v_sub_u32_e32 v35, v35, v32
	v_add_u32_e32 v35, 0x44, v35
	v_med3_f32 v36, v37, v36, v35
	v_med3_f32 v37, v38, v37, v35
	v_med3_f32 v38, v39, v38, v35
	v_med3_f32 v39, v40, v39, v35
	v_med3_f32 v40, v41, v40, v35
	v_med3_f32 v41, v42, v41, v35
	v_med3_f32 v42, v43, v42, v35
	v_med3_f32 v43, v44, v43, v35
	v_med3_f32 v44, v45, v44, v35
	v_med3_f32 v45, v46, v45, v35
	v_med3_f32 v46, v47, v46, v35
	v_med3_f32 v47, v48, v47, v35
	v_med3_f32 v48, v50, v48, v35
	v_med3_f32 v49, v51, v50, v35
	v_med3_f32 v50, v34, v51, v35
	v_max_f32_e32 v35, v35, v35
	v_max_f32_e32 v34, v34, v35
	v_bitop3_b32 v16, v16, 63, v32 bitop3:0x36
	v_med3_f32 v35, v37, v36, v16
	v_med3_f32 v36, v38, v37, v16
	v_med3_f32 v37, v39, v38, v16
	v_med3_f32 v38, v40, v39, v16
	v_med3_f32 v39, v41, v40, v16
	v_med3_f32 v40, v42, v41, v16
	v_med3_f32 v41, v43, v42, v16
	v_med3_f32 v42, v44, v43, v16
	v_med3_f32 v43, v45, v44, v16
	v_med3_f32 v44, v46, v45, v16
	v_med3_f32 v45, v47, v46, v16
	v_med3_f32 v46, v48, v47, v16
	v_med3_f32 v47, v49, v48, v16
	v_med3_f32 v48, v50, v49, v16
	v_med3_f32 v49, v34, v50, v16
	v_max_f32_e32 v16, v16, v16
	v_sub_u32_e32 v17, v17, v32
	v_max_f32_e32 v16, v34, v16
	v_add_u32_e32 v17, 62, v17
	v_med3_f32 v34, v36, v35, v17
	v_med3_f32 v35, v37, v36, v17
	v_med3_f32 v36, v38, v37, v17
	v_med3_f32 v37, v39, v38, v17
	v_med3_f32 v38, v40, v39, v17
	v_med3_f32 v39, v41, v40, v17
	v_med3_f32 v40, v42, v41, v17
	v_med3_f32 v41, v43, v42, v17
	v_med3_f32 v42, v44, v43, v17
	v_med3_f32 v43, v45, v44, v17
	v_med3_f32 v44, v46, v45, v17
	v_med3_f32 v45, v47, v46, v17
	v_med3_f32 v46, v48, v47, v17
	v_med3_f32 v47, v49, v48, v17
	v_med3_f32 v48, v16, v49, v17
	v_max_f32_e32 v17, v17, v17
	v_max_f32_e32 v16, v16, v17
	v_and_b32_e32 v17, 0xffffff80, v18
	v_sub_u32_e32 v17, v17, v32
	v_add_u32_e32 v17, 61, v17
	v_med3_f32 v18, v35, v34, v17
	v_med3_f32 v34, v36, v35, v17
	v_med3_f32 v35, v37, v36, v17
	v_med3_f32 v36, v38, v37, v17
	v_med3_f32 v37, v39, v38, v17
	v_med3_f32 v38, v40, v39, v17
	v_med3_f32 v39, v41, v40, v17
	v_med3_f32 v40, v42, v41, v17
	v_med3_f32 v41, v43, v42, v17
	v_med3_f32 v42, v44, v43, v17
	v_med3_f32 v43, v45, v44, v17
	v_med3_f32 v44, v46, v45, v17
	v_med3_f32 v45, v47, v46, v17
	v_med3_f32 v46, v48, v47, v17
	v_med3_f32 v47, v16, v48, v17
	v_max_f32_e32 v17, v17, v17
	v_max_f32_e32 v16, v16, v17
	v_and_b32_e32 v17, 0xffffff80, v19
	v_sub_u32_e32 v17, v17, v32
	v_add_u32_e32 v17, 60, v17
	v_med3_f32 v18, v34, v18, v17
	v_med3_f32 v19, v35, v34, v17
	v_med3_f32 v34, v36, v35, v17
	v_med3_f32 v35, v37, v36, v17
	v_med3_f32 v36, v38, v37, v17
	v_med3_f32 v37, v39, v38, v17
	v_med3_f32 v38, v40, v39, v17
	v_med3_f32 v39, v41, v40, v17
	v_med3_f32 v40, v42, v41, v17
	v_med3_f32 v41, v43, v42, v17
	v_med3_f32 v42, v44, v43, v17
	v_med3_f32 v43, v45, v44, v17
	v_med3_f32 v44, v46, v45, v17
	v_med3_f32 v45, v47, v46, v17
	v_med3_f32 v46, v16, v47, v17
	v_max_f32_e32 v17, v17, v17
	v_max_f32_e32 v16, v16, v17
	v_and_b32_e32 v17, 0xffffff80, v20
	v_sub_u32_e32 v17, v17, v32
	v_add_u32_e32 v17, 55, v17
	v_med3_f32 v18, v19, v18, v17
	v_med3_f32 v19, v34, v19, v17
	v_med3_f32 v20, v35, v34, v17
	v_med3_f32 v34, v36, v35, v17
	v_med3_f32 v35, v37, v36, v17
	v_med3_f32 v36, v38, v37, v17
	v_med3_f32 v37, v39, v38, v17
	v_med3_f32 v38, v40, v39, v17
	v_med3_f32 v39, v41, v40, v17
	v_med3_f32 v40, v42, v41, v17
	v_med3_f32 v41, v43, v42, v17
	v_med3_f32 v42, v44, v43, v17
	v_med3_f32 v43, v45, v44, v17
	v_med3_f32 v44, v46, v45, v17
	v_med3_f32 v45, v16, v46, v17
	v_max_f32_e32 v17, v17, v17
	v_max_f32_e32 v16, v16, v17
	v_and_b32_e32 v17, 0xffffff80, v21
	v_sub_u32_e32 v17, v17, v32
	v_add_u32_e32 v17, 54, v17
	v_med3_f32 v18, v19, v18, v17
	v_med3_f32 v19, v20, v19, v17
	v_med3_f32 v20, v34, v20, v17
	v_med3_f32 v21, v35, v34, v17
	v_med3_f32 v34, v36, v35, v17
	v_med3_f32 v35, v37, v36, v17
	v_med3_f32 v36, v38, v37, v17
	v_med3_f32 v37, v39, v38, v17
	v_med3_f32 v38, v40, v39, v17
	v_med3_f32 v39, v41, v40, v17
	v_med3_f32 v40, v42, v41, v17
	v_med3_f32 v41, v43, v42, v17
	v_med3_f32 v42, v44, v43, v17
	v_med3_f32 v43, v45, v44, v17
	v_med3_f32 v44, v16, v45, v17
	v_max_f32_e32 v17, v17, v17
	v_max_f32_e32 v16, v16, v17
	v_and_b32_e32 v17, 0xffffff80, v22
	v_sub_u32_e32 v17, v17, v32
	v_add_u32_e32 v17, 53, v17
	v_med3_f32 v18, v19, v18, v17
	v_med3_f32 v19, v20, v19, v17
	v_med3_f32 v20, v21, v20, v17
	v_med3_f32 v21, v34, v21, v17
	v_med3_f32 v22, v35, v34, v17
	v_med3_f32 v34, v36, v35, v17
	v_med3_f32 v35, v37, v36, v17
	v_med3_f32 v36, v38, v37, v17
	v_med3_f32 v37, v39, v38, v17
	v_med3_f32 v38, v40, v39, v17
	v_med3_f32 v39, v41, v40, v17
	v_med3_f32 v40, v42, v41, v17
	v_med3_f32 v41, v43, v42, v17
	v_med3_f32 v42, v44, v43, v17
	v_med3_f32 v43, v16, v44, v17
	v_max_f32_e32 v17, v17, v17
	v_max_f32_e32 v16, v16, v17
	v_and_b32_e32 v17, 0xffffff80, v23
	v_sub_u32_e32 v17, v17, v32
	v_add_u32_e32 v17, 52, v17
	v_med3_f32 v18, v19, v18, v17
	v_med3_f32 v19, v20, v19, v17
	v_med3_f32 v20, v21, v20, v17
	v_med3_f32 v21, v22, v21, v17
	v_med3_f32 v22, v34, v22, v17
	v_med3_f32 v23, v35, v34, v17
	v_med3_f32 v34, v36, v35, v17
	v_med3_f32 v35, v37, v36, v17
	v_med3_f32 v36, v38, v37, v17
	v_med3_f32 v37, v39, v38, v17
	v_med3_f32 v38, v40, v39, v17
	v_med3_f32 v39, v41, v40, v17
	v_med3_f32 v40, v42, v41, v17
	v_med3_f32 v41, v43, v42, v17
	v_med3_f32 v42, v16, v43, v17
	v_max_f32_e32 v17, v17, v17
	v_max_f32_e32 v16, v16, v17
	v_and_b32_e32 v17, 0xffffff80, v24
	v_sub_u32_e32 v17, v17, v32
	v_add_u32_e32 v17, 47, v17
	v_med3_f32 v18, v19, v18, v17
	v_med3_f32 v19, v20, v19, v17
	v_med3_f32 v20, v21, v20, v17
	v_med3_f32 v21, v22, v21, v17
	v_med3_f32 v22, v23, v22, v17
	v_med3_f32 v23, v34, v23, v17
	v_med3_f32 v24, v35, v34, v17
	v_med3_f32 v34, v36, v35, v17
	v_med3_f32 v35, v37, v36, v17
	v_med3_f32 v36, v38, v37, v17
	v_med3_f32 v37, v39, v38, v17
	v_med3_f32 v38, v40, v39, v17
	v_med3_f32 v39, v41, v40, v17
	v_med3_f32 v40, v42, v41, v17
	v_med3_f32 v41, v16, v42, v17
	v_max_f32_e32 v17, v17, v17
	v_max_f32_e32 v16, v16, v17
	v_and_b32_e32 v17, 0xffffff80, v25
	v_sub_u32_e32 v17, v17, v32
	v_add_u32_e32 v17, 46, v17
	v_med3_f32 v18, v19, v18, v17
	v_med3_f32 v19, v20, v19, v17
	v_med3_f32 v20, v21, v20, v17
	v_med3_f32 v21, v22, v21, v17
	v_med3_f32 v22, v23, v22, v17
	v_med3_f32 v23, v24, v23, v17
	v_med3_f32 v24, v34, v24, v17
	v_med3_f32 v25, v35, v34, v17
	v_med3_f32 v34, v36, v35, v17
	v_med3_f32 v35, v37, v36, v17
	v_med3_f32 v36, v38, v37, v17
	v_med3_f32 v37, v39, v38, v17
	v_med3_f32 v38, v40, v39, v17
	v_med3_f32 v39, v41, v40, v17
	v_med3_f32 v40, v16, v41, v17
	v_max_f32_e32 v17, v17, v17
	v_max_f32_e32 v16, v16, v17
	v_and_b32_e32 v17, 0xffffff80, v26
	v_sub_u32_e32 v17, v17, v32
	v_add_u32_e32 v17, 45, v17
	v_med3_f32 v18, v19, v18, v17
	v_med3_f32 v19, v20, v19, v17
	v_med3_f32 v20, v21, v20, v17
	v_med3_f32 v21, v22, v21, v17
	v_med3_f32 v22, v23, v22, v17
	v_med3_f32 v23, v24, v23, v17
	v_med3_f32 v24, v25, v24, v17
	v_med3_f32 v25, v34, v25, v17
	v_med3_f32 v26, v35, v34, v17
	v_med3_f32 v34, v36, v35, v17
	v_med3_f32 v35, v37, v36, v17
	v_med3_f32 v36, v38, v37, v17
	v_med3_f32 v37, v39, v38, v17
	v_med3_f32 v38, v40, v39, v17
	v_med3_f32 v39, v16, v40, v17
	v_max_f32_e32 v17, v17, v17
	v_max_f32_e32 v16, v16, v17
	v_and_b32_e32 v17, 0xffffff80, v27
	v_sub_u32_e32 v17, v17, v32
	v_add_u32_e32 v17, 44, v17
	v_med3_f32 v18, v19, v18, v17
	v_med3_f32 v19, v20, v19, v17
	v_med3_f32 v20, v21, v20, v17
	v_med3_f32 v21, v22, v21, v17
	v_med3_f32 v22, v23, v22, v17
	v_med3_f32 v23, v24, v23, v17
	v_med3_f32 v24, v25, v24, v17
	v_med3_f32 v25, v26, v25, v17
	v_med3_f32 v26, v34, v26, v17
	v_med3_f32 v27, v35, v34, v17
	v_med3_f32 v34, v36, v35, v17
	v_med3_f32 v35, v37, v36, v17
	v_med3_f32 v36, v38, v37, v17
	v_med3_f32 v37, v39, v38, v17
	v_med3_f32 v38, v16, v39, v17
	v_max_f32_e32 v17, v17, v17
	v_max_f32_e32 v16, v16, v17
	v_and_b32_e32 v17, 0xffffff80, v28
	v_sub_u32_e32 v17, v17, v32
	v_add_u32_e32 v17, 39, v17
	v_med3_f32 v18, v19, v18, v17
	v_med3_f32 v19, v20, v19, v17
	v_med3_f32 v20, v21, v20, v17
	v_med3_f32 v21, v22, v21, v17
	v_med3_f32 v22, v23, v22, v17
	v_med3_f32 v23, v24, v23, v17
	v_med3_f32 v24, v25, v24, v17
	v_med3_f32 v25, v26, v25, v17
	v_med3_f32 v26, v27, v26, v17
	v_med3_f32 v27, v34, v27, v17
	v_med3_f32 v28, v35, v34, v17
	v_med3_f32 v34, v36, v35, v17
	v_med3_f32 v35, v37, v36, v17
	v_med3_f32 v36, v38, v37, v17
	v_med3_f32 v37, v16, v38, v17
	v_max_f32_e32 v17, v17, v17
	v_max_f32_e32 v16, v16, v17
	v_and_b32_e32 v17, 0xffffff80, v29
	v_sub_u32_e32 v17, v17, v32
	v_add_u32_e32 v17, 38, v17
	v_med3_f32 v18, v19, v18, v17
	v_med3_f32 v19, v20, v19, v17
	v_med3_f32 v20, v21, v20, v17
	v_med3_f32 v21, v22, v21, v17
	v_med3_f32 v22, v23, v22, v17
	v_med3_f32 v23, v24, v23, v17
	v_med3_f32 v24, v25, v24, v17
	v_med3_f32 v25, v26, v25, v17
	v_med3_f32 v26, v27, v26, v17
	v_med3_f32 v27, v28, v27, v17
	v_med3_f32 v28, v34, v28, v17
	v_med3_f32 v29, v35, v34, v17
	v_med3_f32 v34, v36, v35, v17
	v_med3_f32 v35, v37, v36, v17
	v_med3_f32 v36, v16, v37, v17
	v_max_f32_e32 v17, v17, v17
	v_max_f32_e32 v16, v16, v17
	v_and_b32_e32 v17, 0xffffff80, v30
	v_sub_u32_e32 v17, v17, v32
	v_add_u32_e32 v17, 37, v17
	v_med3_f32 v18, v19, v18, v17
	v_med3_f32 v19, v20, v19, v17
	v_med3_f32 v20, v21, v20, v17
	v_med3_f32 v21, v22, v21, v17
	v_med3_f32 v22, v23, v22, v17
	v_med3_f32 v23, v24, v23, v17
	v_med3_f32 v24, v25, v24, v17
	v_med3_f32 v25, v26, v25, v17
	v_med3_f32 v26, v27, v26, v17
	v_med3_f32 v27, v28, v27, v17
	v_med3_f32 v28, v29, v28, v17
	v_med3_f32 v29, v34, v29, v17
	v_med3_f32 v30, v35, v34, v17
	v_med3_f32 v34, v36, v35, v17
	v_med3_f32 v35, v16, v36, v17
	v_max_f32_e32 v17, v17, v17
	v_max_f32_e32 v16, v16, v17
	v_and_b32_e32 v17, 0xffffff80, v31
	v_sub_u32_e32 v17, v17, v32
	v_add_u32_e32 v17, 36, v17
	v_med3_f32 v18, v19, v18, v17
	v_med3_f32 v19, v20, v19, v17
	v_med3_f32 v20, v21, v20, v17
	v_med3_f32 v21, v22, v21, v17
	v_med3_f32 v22, v23, v22, v17
	v_med3_f32 v23, v24, v23, v17
	v_med3_f32 v24, v25, v24, v17
	v_med3_f32 v25, v26, v25, v17
	v_med3_f32 v26, v27, v26, v17
	v_med3_f32 v27, v28, v27, v17
	v_med3_f32 v28, v29, v28, v17
	v_med3_f32 v29, v30, v29, v17
	v_med3_f32 v30, v34, v30, v17
	v_med3_f32 v31, v35, v34, v17
	v_med3_f32 v34, v16, v35, v17
	v_max_f32_e32 v17, v17, v17
	v_and_b32_e32 v0, 0xffffff80, v0
	v_max_f32_e32 v16, v16, v17
	v_bitop3_b32 v0, v0, 31, v32 bitop3:0x36
	v_and_b32_e32 v1, 0xffffff80, v1
	v_med3_f32 v17, v19, v18, v0
	v_med3_f32 v18, v20, v19, v0
	v_med3_f32 v19, v21, v20, v0
	v_med3_f32 v20, v22, v21, v0
	v_med3_f32 v21, v23, v22, v0
	v_med3_f32 v22, v24, v23, v0
	v_med3_f32 v23, v25, v24, v0
	v_med3_f32 v24, v26, v25, v0
	v_med3_f32 v25, v27, v26, v0
	v_med3_f32 v26, v28, v27, v0
	v_med3_f32 v27, v29, v28, v0
	v_med3_f32 v28, v30, v29, v0
	v_med3_f32 v29, v31, v30, v0
	v_med3_f32 v30, v34, v31, v0
	v_med3_f32 v31, v16, v34, v0
	v_max_f32_e32 v0, v0, v0
	v_sub_u32_e32 v1, v1, v32
	v_max_f32_e32 v0, v16, v0
	v_add_u32_e32 v1, 30, v1
	v_med3_f32 v16, v18, v17, v1
	v_med3_f32 v17, v19, v18, v1
	v_med3_f32 v18, v20, v19, v1
	v_med3_f32 v19, v21, v20, v1
	v_med3_f32 v20, v22, v21, v1
	v_med3_f32 v21, v23, v22, v1
	v_med3_f32 v22, v24, v23, v1
	v_med3_f32 v23, v25, v24, v1
	v_med3_f32 v24, v26, v25, v1
	v_med3_f32 v25, v27, v26, v1
	v_med3_f32 v26, v28, v27, v1
	v_med3_f32 v27, v29, v28, v1
	v_med3_f32 v28, v30, v29, v1
	v_med3_f32 v29, v31, v30, v1
	v_med3_f32 v30, v0, v31, v1
	v_max_f32_e32 v1, v1, v1
	v_max_f32_e32 v0, v0, v1
	v_and_b32_e32 v1, 0xffffff80, v2
	v_sub_u32_e32 v1, v1, v32
	v_add_u32_e32 v1, 29, v1
	v_med3_f32 v2, v17, v16, v1
	v_med3_f32 v16, v18, v17, v1
	v_med3_f32 v17, v19, v18, v1
	v_med3_f32 v18, v20, v19, v1
	v_med3_f32 v19, v21, v20, v1
	v_med3_f32 v20, v22, v21, v1
	v_med3_f32 v21, v23, v22, v1
	v_med3_f32 v22, v24, v23, v1
	v_med3_f32 v23, v25, v24, v1
	v_med3_f32 v24, v26, v25, v1
	v_med3_f32 v25, v27, v26, v1
	v_med3_f32 v26, v28, v27, v1
	v_med3_f32 v27, v29, v28, v1
	v_med3_f32 v28, v30, v29, v1
	v_med3_f32 v29, v0, v30, v1
	v_max_f32_e32 v1, v1, v1
	v_max_f32_e32 v0, v0, v1
	v_and_b32_e32 v1, 0xffffff80, v3
	v_sub_u32_e32 v1, v1, v32
	v_add_u32_e32 v1, 28, v1
	v_med3_f32 v2, v16, v2, v1
	v_med3_f32 v3, v17, v16, v1
	v_med3_f32 v16, v18, v17, v1
	v_med3_f32 v17, v19, v18, v1
	v_med3_f32 v18, v20, v19, v1
	v_med3_f32 v19, v21, v20, v1
	v_med3_f32 v20, v22, v21, v1
	v_med3_f32 v21, v23, v22, v1
	v_med3_f32 v22, v24, v23, v1
	v_med3_f32 v23, v25, v24, v1
	v_med3_f32 v24, v26, v25, v1
	v_med3_f32 v25, v27, v26, v1
	v_med3_f32 v26, v28, v27, v1
	v_med3_f32 v27, v29, v28, v1
	v_med3_f32 v28, v0, v29, v1
	v_max_f32_e32 v1, v1, v1
	v_max_f32_e32 v0, v0, v1
	v_and_b32_e32 v1, 0xffffff80, v4
	v_sub_u32_e32 v1, v1, v32
	v_add_u32_e32 v1, 23, v1
	v_med3_f32 v2, v3, v2, v1
	v_med3_f32 v3, v16, v3, v1
	v_med3_f32 v4, v17, v16, v1
	v_med3_f32 v16, v18, v17, v1
	v_med3_f32 v17, v19, v18, v1
	v_med3_f32 v18, v20, v19, v1
	v_med3_f32 v19, v21, v20, v1
	v_med3_f32 v20, v22, v21, v1
	v_med3_f32 v21, v23, v22, v1
	v_med3_f32 v22, v24, v23, v1
	v_med3_f32 v23, v25, v24, v1
	v_med3_f32 v24, v26, v25, v1
	v_med3_f32 v25, v27, v26, v1
	v_med3_f32 v26, v28, v27, v1
	v_med3_f32 v27, v0, v28, v1
	v_max_f32_e32 v1, v1, v1
	v_max_f32_e32 v0, v0, v1
	v_and_b32_e32 v1, 0xffffff80, v5
	v_sub_u32_e32 v1, v1, v32
	v_add_u32_e32 v1, 22, v1
	v_med3_f32 v2, v3, v2, v1
	v_med3_f32 v3, v4, v3, v1
	v_med3_f32 v4, v16, v4, v1
	v_med3_f32 v5, v17, v16, v1
	v_med3_f32 v16, v18, v17, v1
	v_med3_f32 v17, v19, v18, v1
	v_med3_f32 v18, v20, v19, v1
	v_med3_f32 v19, v21, v20, v1
	v_med3_f32 v20, v22, v21, v1
	v_med3_f32 v21, v23, v22, v1
	v_med3_f32 v22, v24, v23, v1
	v_med3_f32 v23, v25, v24, v1
	v_med3_f32 v24, v26, v25, v1
	v_med3_f32 v25, v27, v26, v1
	v_med3_f32 v26, v0, v27, v1
	v_max_f32_e32 v1, v1, v1
	v_max_f32_e32 v0, v0, v1
	v_and_b32_e32 v1, 0xffffff80, v6
	v_sub_u32_e32 v1, v1, v32
	v_add_u32_e32 v1, 21, v1
	v_med3_f32 v2, v3, v2, v1
	v_med3_f32 v3, v4, v3, v1
	v_med3_f32 v4, v5, v4, v1
	v_med3_f32 v5, v16, v5, v1
	v_med3_f32 v6, v17, v16, v1
	v_med3_f32 v16, v18, v17, v1
	v_med3_f32 v17, v19, v18, v1
	v_med3_f32 v18, v20, v19, v1
	v_med3_f32 v19, v21, v20, v1
	v_med3_f32 v20, v22, v21, v1
	v_med3_f32 v21, v23, v22, v1
	v_med3_f32 v22, v24, v23, v1
	v_med3_f32 v23, v25, v24, v1
	v_med3_f32 v24, v26, v25, v1
	v_med3_f32 v25, v0, v26, v1
	v_max_f32_e32 v1, v1, v1
	v_max_f32_e32 v0, v0, v1
	v_and_b32_e32 v1, 0xffffff80, v7
	v_sub_u32_e32 v1, v1, v32
	v_add_u32_e32 v1, 20, v1
	v_med3_f32 v2, v3, v2, v1
	v_med3_f32 v3, v4, v3, v1
	v_med3_f32 v4, v5, v4, v1
	v_med3_f32 v5, v6, v5, v1
	v_med3_f32 v6, v16, v6, v1
	v_med3_f32 v7, v17, v16, v1
	v_med3_f32 v16, v18, v17, v1
	v_med3_f32 v17, v19, v18, v1
	v_med3_f32 v18, v20, v19, v1
	v_med3_f32 v19, v21, v20, v1
	v_med3_f32 v20, v22, v21, v1
	v_med3_f32 v21, v23, v22, v1
	v_med3_f32 v22, v24, v23, v1
	v_med3_f32 v23, v25, v24, v1
	v_med3_f32 v24, v0, v25, v1
	v_max_f32_e32 v1, v1, v1
	v_max_f32_e32 v0, v0, v1
	v_and_b32_e32 v1, 0xffffff80, v8
	v_bitop3_b32 v1, v1, 15, v32 bitop3:0x36
	v_med3_f32 v2, v3, v2, v1
	v_med3_f32 v3, v4, v3, v1
	v_med3_f32 v4, v5, v4, v1
	v_med3_f32 v5, v6, v5, v1
	v_med3_f32 v6, v7, v6, v1
	v_med3_f32 v7, v16, v7, v1
	v_med3_f32 v8, v17, v16, v1
	v_med3_f32 v16, v18, v17, v1
	v_med3_f32 v17, v19, v18, v1
	v_med3_f32 v18, v20, v19, v1
	v_med3_f32 v19, v21, v20, v1
	v_med3_f32 v20, v22, v21, v1
	v_med3_f32 v21, v23, v22, v1
	v_med3_f32 v22, v24, v23, v1
	v_med3_f32 v23, v0, v24, v1
	v_max_f32_e32 v1, v1, v1
	v_max_f32_e32 v0, v0, v1
	v_and_b32_e32 v1, 0xffffff80, v9
	v_sub_u32_e32 v1, v1, v32
	v_add_u32_e32 v1, 14, v1
	v_med3_f32 v2, v3, v2, v1
	v_med3_f32 v3, v4, v3, v1
	v_med3_f32 v4, v5, v4, v1
	v_med3_f32 v5, v6, v5, v1
	v_med3_f32 v6, v7, v6, v1
	v_med3_f32 v7, v8, v7, v1
	v_med3_f32 v8, v16, v8, v1
	v_med3_f32 v9, v17, v16, v1
	v_med3_f32 v16, v18, v17, v1
	v_med3_f32 v17, v19, v18, v1
	v_med3_f32 v18, v20, v19, v1
	v_med3_f32 v19, v21, v20, v1
	v_med3_f32 v20, v22, v21, v1
	v_med3_f32 v21, v23, v22, v1
	v_med3_f32 v22, v0, v23, v1
	v_max_f32_e32 v1, v1, v1
	v_max_f32_e32 v0, v0, v1
	v_and_b32_e32 v1, 0xffffff80, v10
	v_sub_u32_e32 v1, v1, v32
	v_add_u32_e32 v1, 13, v1
	v_med3_f32 v2, v3, v2, v1
	v_med3_f32 v3, v4, v3, v1
	v_med3_f32 v4, v5, v4, v1
	v_med3_f32 v5, v6, v5, v1
	v_med3_f32 v6, v7, v6, v1
	v_med3_f32 v7, v8, v7, v1
	v_med3_f32 v8, v9, v8, v1
	v_med3_f32 v9, v16, v9, v1
	v_med3_f32 v10, v17, v16, v1
	v_med3_f32 v16, v18, v17, v1
	v_med3_f32 v17, v19, v18, v1
	v_med3_f32 v18, v20, v19, v1
	v_med3_f32 v19, v21, v20, v1
	v_med3_f32 v20, v22, v21, v1
	v_med3_f32 v21, v0, v22, v1
	v_max_f32_e32 v1, v1, v1
	v_max_f32_e32 v0, v0, v1
	v_and_b32_e32 v1, 0xffffff80, v11
	v_sub_u32_e32 v1, v1, v32
	v_add_u32_e32 v1, 12, v1
	v_med3_f32 v2, v3, v2, v1
	v_med3_f32 v3, v4, v3, v1
	v_med3_f32 v4, v5, v4, v1
	v_med3_f32 v5, v6, v5, v1
	v_med3_f32 v6, v7, v6, v1
	v_med3_f32 v7, v8, v7, v1
	v_med3_f32 v8, v9, v8, v1
	v_med3_f32 v9, v10, v9, v1
	v_med3_f32 v10, v16, v10, v1
	v_med3_f32 v11, v17, v16, v1
	v_med3_f32 v16, v18, v17, v1
	v_med3_f32 v17, v19, v18, v1
	v_med3_f32 v18, v20, v19, v1
	v_med3_f32 v19, v21, v20, v1
	v_med3_f32 v20, v0, v21, v1
	v_max_f32_e32 v1, v1, v1
	v_max_f32_e32 v0, v0, v1
	v_and_b32_e32 v1, 0xffffff80, v12
	v_bitop3_b32 v1, v1, 7, v32 bitop3:0x36
	v_med3_f32 v2, v3, v2, v1
	v_med3_f32 v3, v4, v3, v1
	v_med3_f32 v4, v5, v4, v1
	v_med3_f32 v5, v6, v5, v1
	v_med3_f32 v6, v7, v6, v1
	v_med3_f32 v7, v8, v7, v1
	v_med3_f32 v8, v9, v8, v1
	v_med3_f32 v9, v10, v9, v1
	v_med3_f32 v10, v11, v10, v1
	v_med3_f32 v11, v16, v11, v1
	v_med3_f32 v12, v17, v16, v1
	v_med3_f32 v16, v18, v17, v1
	v_med3_f32 v17, v19, v18, v1
	v_med3_f32 v18, v20, v19, v1
	v_med3_f32 v19, v0, v20, v1
	v_max_f32_e32 v1, v1, v1
	v_max_f32_e32 v0, v0, v1
	v_and_b32_e32 v1, 0xffffff80, v13
	v_sub_u32_e32 v1, v1, v32
	v_add_u32_e32 v1, 6, v1
	v_med3_f32 v2, v3, v2, v1
	v_med3_f32 v3, v4, v3, v1
	v_med3_f32 v4, v5, v4, v1
	v_med3_f32 v5, v6, v5, v1
	v_med3_f32 v6, v7, v6, v1
	v_med3_f32 v7, v8, v7, v1
	v_med3_f32 v8, v9, v8, v1
	v_med3_f32 v9, v10, v9, v1
	v_med3_f32 v10, v11, v10, v1
	v_med3_f32 v11, v12, v11, v1
	v_med3_f32 v12, v16, v12, v1
	v_med3_f32 v13, v17, v16, v1
	v_med3_f32 v16, v18, v17, v1
	v_med3_f32 v17, v19, v18, v1
	v_med3_f32 v18, v0, v19, v1
	v_max_f32_e32 v1, v1, v1
	v_max_f32_e32 v0, v0, v1
	v_and_b32_e32 v1, 0xffffff80, v14
	v_sub_u32_e32 v1, v1, v32
	v_add_u32_e32 v1, 5, v1
	v_med3_f32 v2, v3, v2, v1
	v_med3_f32 v3, v4, v3, v1
	v_med3_f32 v14, v5, v4, v1
	v_med3_f32 v19, v6, v5, v1
	v_med3_f32 v20, v7, v6, v1
	v_med3_f32 v7, v8, v7, v1
	v_med3_f32 v8, v9, v8, v1
	v_med3_f32 v9, v10, v9, v1
	v_med3_f32 v10, v11, v10, v1
	v_med3_f32 v11, v12, v11, v1
	v_med3_f32 v12, v13, v12, v1
	v_med3_f32 v13, v16, v13, v1
	v_med3_f32 v16, v17, v16, v1
	v_med3_f32 v17, v18, v17, v1
	v_med3_f32 v18, v0, v18, v1
	v_max_f32_e32 v1, v1, v1
	v_max_f32_e32 v0, v0, v1
	v_and_b32_e32 v1, 0xffffff80, v15
	v_sub_u32_e32 v1, v1, v32
	v_add_u32_e32 v1, 4, v1
	v_med3_f32 v4, v3, v2, v1
	v_med3_f32 v5, v14, v3, v1
	v_med3_f32 v6, v19, v14, v1
	v_med3_f32 v23, v20, v19, v1
	v_med3_f32 v24, v7, v20, v1
	v_med3_f32 v25, v8, v7, v1
	v_med3_f32 v26, v9, v8, v1
	v_med3_f32 v27, v10, v9, v1
	v_med3_f32 v28, v11, v10, v1
	v_med3_f32 v29, v12, v11, v1
	v_med3_f32 v30, v13, v12, v1
	v_med3_f32 v31, v16, v13, v1
	v_med3_f32 v32, v17, v16, v1
	v_med3_f32 v3, v18, v17, v1
	v_med3_f32 v2, v0, v18, v1
	v_max_f32_e32 v1, v1, v1
	v_and_b32_e32 v7, 64, v214
	v_max_f32_e32 v1, v0, v1
	v_xor_b32_e32 v0, 32, v214
	v_add_u32_e32 v7, 64, v7
	v_cmp_lt_i32_e32 vcc, v0, v7
	s_nop 1
	v_cndmask_b32_e32 v0, v214, v0, vcc
	v_lshlrev_b32_e32 v0, 2, v0
	ds_bpermute_b32 v7, v0, v1
	ds_bpermute_b32 v8, v0, v2
	ds_bpermute_b32 v9, v0, v3
	ds_bpermute_b32 v10, v0, v32
	ds_bpermute_b32 v11, v0, v31
	ds_bpermute_b32 v12, v0, v30
	ds_bpermute_b32 v13, v0, v29
	ds_bpermute_b32 v14, v0, v28
	ds_bpermute_b32 v15, v0, v27
	ds_bpermute_b32 v16, v0, v26
	ds_bpermute_b32 v17, v0, v25
	ds_bpermute_b32 v18, v0, v24
	ds_bpermute_b32 v19, v0, v23
	ds_bpermute_b32 v20, v0, v6
	ds_bpermute_b32 v21, v0, v5
	ds_bpermute_b32 v22, v0, v4
	v_cmp_gt_u32_e32 vcc, 32, v130
	s_and_saveexec_b64 s[8:9], vcc
	s_cbranch_execz .LBB0_1861
	s_waitcnt lgkmcnt(0)
	v_max_f32_e32 v34, v1, v22
	v_max_f32_e32 v35, v2, v21
	v_max_f32_e32 v36, v3, v20
	v_max_f32_e32 v37, v32, v19
	v_max_f32_e32 v38, v31, v18
	v_max_f32_e32 v39, v30, v17
	v_max_f32_e32 v40, v29, v16
	v_max_f32_e32 v41, v28, v15
	v_max_f32_e32 v42, v27, v14
	v_max_f32_e32 v43, v26, v13
	v_max_f32_e32 v44, v25, v12
	v_max_f32_e32 v45, v24, v11
	v_max_f32_e32 v46, v23, v10
	v_max_f32_e32 v47, v6, v9
	v_max_f32_e32 v48, v5, v8
	v_max_f32_e32 v49, v4, v7
	v_max_f32_e32 v7, v34, v42
	v_min_f32_e32 v15, v34, v42
	v_max_f32_e32 v8, v35, v43
	v_min_f32_e32 v16, v35, v43
	v_max_f32_e32 v9, v36, v44
	v_min_f32_e32 v17, v36, v44
	v_max_f32_e32 v10, v37, v45
	v_min_f32_e32 v18, v37, v45
	v_max_f32_e32 v11, v38, v46
	v_min_f32_e32 v19, v38, v46
	v_max_f32_e32 v12, v39, v47
	v_min_f32_e32 v20, v39, v47
	v_max_f32_e32 v13, v40, v48
	v_min_f32_e32 v21, v40, v48
	v_max_f32_e32 v14, v41, v49
	v_min_f32_e32 v22, v41, v49
	v_max_f32_e32 v34, v7, v11
	v_min_f32_e32 v38, v7, v11
	v_max_f32_e32 v35, v8, v12
	v_min_f32_e32 v39, v8, v12
	v_max_f32_e32 v36, v9, v13
	v_min_f32_e32 v40, v9, v13
	v_max_f32_e32 v37, v10, v14
	v_min_f32_e32 v41, v10, v14
	v_max_f32_e32 v42, v15, v19
	v_min_f32_e32 v46, v15, v19
	v_max_f32_e32 v43, v16, v20
	v_min_f32_e32 v47, v16, v20
	v_max_f32_e32 v44, v17, v21
	v_min_f32_e32 v48, v17, v21
	v_max_f32_e32 v45, v18, v22
	v_min_f32_e32 v49, v18, v22
	v_max_f32_e32 v7, v34, v36
	v_min_f32_e32 v9, v34, v36
	v_max_f32_e32 v8, v35, v37
	v_min_f32_e32 v10, v35, v37
	v_max_f32_e32 v11, v38, v40
	v_min_f32_e32 v13, v38, v40
	v_max_f32_e32 v12, v39, v41
	v_min_f32_e32 v14, v39, v41
	v_max_f32_e32 v15, v42, v44
	v_min_f32_e32 v17, v42, v44
	v_max_f32_e32 v16, v43, v45
	v_min_f32_e32 v18, v43, v45
	v_max_f32_e32 v19, v46, v48
	v_min_f32_e32 v21, v46, v48
	v_max_f32_e32 v20, v47, v49
	v_min_f32_e32 v22, v47, v49
	v_max_f32_e32 v0, v7, v8
	v_min_f32_e32 v1, v7, v8
	v_max_f32_e32 v2, v9, v10
	v_min_f32_e32 v3, v9, v10
	v_max_f32_e32 v34, v11, v12
	v_min_f32_e32 v35, v11, v12
	v_max_f32_e32 v36, v13, v14
	v_min_f32_e32 v37, v13, v14
	v_max_f32_e32 v28, v15, v16
	v_min_f32_e32 v29, v15, v16
	v_max_f32_e32 v30, v17, v18
	v_min_f32_e32 v31, v17, v18
	v_max_f32_e32 v24, v19, v20
	v_min_f32_e32 v25, v19, v20
	v_max_f32_e32 v26, v21, v22
	v_min_f32_e32 v27, v21, v22
	v_ashrrev_i32_e32 v4, 1, v186
	v_and_b32_e32 v4, 0xffffffe0, v4
	v_lshl_add_u32 v4, s2, 7, v4
	v_or_b32_e32 v4, v4, v130
	v_ashrrev_i32_e32 v5, 31, v4
	v_readlane_b32 s20, v248, 0
	v_lshlrev_b64 v[4:5], 10, v[4:5]
	v_readlane_b32 s21, v248, 1
	s_lshl_b64 s[4:5], s[4:5], 6
	v_lshl_add_u64 v[4:5], s[20:21], 0, v[4:5]
	v_readlane_b32 s20, v249, 14
	v_readlane_b32 s21, v249, 15
	v_lshl_add_u64 v[4:5], v[4:5], 0, s[4:5]
	v_readlane_b32 s22, v248, 2
	v_readlane_b32 s23, v248, 3
	v_readlane_b32 s24, v248, 4
	v_readlane_b32 s25, v248, 5
	v_readlane_b32 s26, v248, 6
	v_readlane_b32 s27, v248, 7
	global_store_dwordx4 v[4:5], v[0:3], off
	global_store_dwordx4 v[4:5], v[34:37], off offset:16
	global_store_dwordx4 v[4:5], v[28:31], off offset:32
	global_store_dwordx4 v[4:5], v[24:27], off offset:48
